# attention QK^T: K-fragment ds_read_b128 issued 8 (s0 chain) / 4 (s1 chain) reads ahead into spare quads with counted lgkmcnt; on top of packed forward substitution and DPP wave sums
# speedup vs baseline: 1.0072x; 1.0042x over previous
; #define LAS __attribute__((address_space(3)))
; DI void attn_item(LAS unsigned char* lds, const Ctx& c, int bh, int qb) {
;     ...
;             const LAS unsigned char* Kb = lds + AT_K + bf * AT_KSZ; const LAS unsigned char* Vb = lds + AT_V + bf * AT_VSZ;
;             f32x16 s0, s1;
; #pragma unroll
;             for (int r = 0; r < 16; ++r) { s0[r] = 0.f; s1[r] = 0.f; }
; #pragma unroll
;             for (int t = 0; t < 12; ++t) {
;                 const bf16x8 k0 = *(const LAS bf16x8*)(Kb + q * 400 + (16 * t + 8 * g) * 2);
;                 const bf16x8 k1 = *(const LAS bf16x8*)(Kb + (32 + q) * 400 + (16 * t + 8 * g) * 2);
;                 s0 = __builtin_amdgcn_mfma_f32_32x32x16_bf16(k0, qf[t], s0, 0, 0, 0);
;                 s1 = __builtin_amdgcn_mfma_f32_32x32x16_bf16(k1, qf[t], s1, 0, 0, 0);
;             }
;             float mx = s0[0];
; #pragma unroll
;             for (int r = 1; r < 16; ++r) mx = fmaxf(mx, s0[r]);
; #pragma unroll
;             for (int r = 0; r < 16; ++r) mx = fmaxf(mx, s1[r]);
;             mx = fmaxf(mx, __shfl_xor(mx, 32));
.LBB0_187:
	s_mul_i32 s14, s11, 0x6400
	v_add_u32_e32 v0, s14, v216
	ds_read_b128 v[66:69], v0
	ds_read_b128 v[70:73], v0 offset:32
	ds_read_b128 v[74:77], v0 offset:64
	ds_read_b128 v[78:81], v0 offset:96
	ds_read_b128 v[220:223], v0 offset:128
	ds_read_b128 v[236:239], v0 offset:160
	ds_read_b128 v[240:243], v0 offset:192
	ds_read_b128 v[244:247], v0 offset:224
	v_and_b32_e32 v199, 64, v230
	v_add_u32_e32 v199, 64, v199
	s_mul_i32 s14, s11, 0x4400
	s_waitcnt lgkmcnt(7)
	v_mfma_f32_32x32x16_bf16 v[82:97], v[66:69], v[98:101], 0
	ds_read_b128 v[66:69], v0 offset:256
	v_add_u32_e32 v224, s14, v217
	v_add_u32_e32 v225, 0xc800, v224
	v_add_u32_e32 v226, 0xd800, v224
	v_add_u32_e32 v228, 0xe800, v224
	v_add_u32_e32 v224, 0xf800, v224
	s_waitcnt lgkmcnt(7)
	v_mfma_f32_32x32x16_bf16 v[82:97], v[70:73], v[102:105], v[82:97]
	ds_read_b128 v[70:73], v0 offset:288
	s_waitcnt lgkmcnt(7)
	v_mfma_f32_32x32x16_bf16 v[82:97], v[74:77], v[106:109], v[82:97]
	ds_read_b128 v[74:77], v0 offset:320
	s_waitcnt lgkmcnt(7)
	v_mfma_f32_32x32x16_bf16 v[82:97], v[78:81], v[110:113], v[82:97]
	ds_read_b128 v[78:81], v0 offset:352
	s_waitcnt lgkmcnt(7)
	v_mfma_f32_32x32x16_bf16 v[82:97], v[220:223], v[114:117], v[82:97]
	ds_read_b128 v[220:223], v0 offset:12800
	s_waitcnt lgkmcnt(7)
	v_mfma_f32_32x32x16_bf16 v[82:97], v[236:239], v[118:121], v[82:97]
	ds_read_b128 v[236:239], v0 offset:12832
	s_waitcnt lgkmcnt(7)
	v_mfma_f32_32x32x16_bf16 v[82:97], v[240:243], v[122:125], v[82:97]
	ds_read_b128 v[240:243], v0 offset:12864
	s_waitcnt lgkmcnt(7)
	v_mfma_f32_32x32x16_bf16 v[82:97], v[244:247], v[126:129], v[82:97]
	ds_read_b128 v[244:247], v0 offset:12896
	s_waitcnt lgkmcnt(7)
	v_mfma_f32_32x32x16_bf16 v[82:97], v[66:69], v[134:137], v[82:97]
	s_waitcnt lgkmcnt(6)
	v_mfma_f32_32x32x16_bf16 v[82:97], v[70:73], v[138:141], v[82:97]
	s_waitcnt lgkmcnt(5)
	v_mfma_f32_32x32x16_bf16 v[82:97], v[74:77], v[142:145], v[82:97]
	s_waitcnt lgkmcnt(4)
	v_mfma_f32_32x32x16_bf16 v[82:97], v[78:81], v[146:149], v[82:97]
	s_waitcnt lgkmcnt(3)
	v_mfma_f32_32x32x16_bf16 v[66:81], v[220:223], v[98:101], 0
	ds_read_b128 v[220:223], v0 offset:12928
	s_nop 9
	v_max_f32_e32 v198, v82, v82
	s_waitcnt lgkmcnt(3)
	v_mfma_f32_32x32x16_bf16 v[66:81], v[236:239], v[102:105], v[66:81]
	ds_read_b128 v[236:239], v0 offset:12960
	s_waitcnt lgkmcnt(3)
	v_mfma_f32_32x32x16_bf16 v[66:81], v[240:243], v[106:109], v[66:81]
	ds_read_b128 v[240:243], v0 offset:12992
	s_waitcnt lgkmcnt(3)
	v_mfma_f32_32x32x16_bf16 v[66:81], v[244:247], v[110:113], v[66:81]
	ds_read_b128 v[244:247], v0 offset:13024
	s_waitcnt lgkmcnt(3)
	v_mfma_f32_32x32x16_bf16 v[66:81], v[220:223], v[114:117], v[66:81]
	ds_read_b128 v[220:223], v0 offset:13056
	s_waitcnt lgkmcnt(3)
	v_mfma_f32_32x32x16_bf16 v[66:81], v[236:239], v[118:121], v[66:81]
	ds_read_b128 v[236:239], v0 offset:13088
	s_waitcnt lgkmcnt(3)
	v_mfma_f32_32x32x16_bf16 v[66:81], v[240:243], v[122:125], v[66:81]
	s_waitcnt lgkmcnt(2)
	v_mfma_f32_32x32x16_bf16 v[66:81], v[244:247], v[126:129], v[66:81]
	s_waitcnt lgkmcnt(1)
	v_mfma_f32_32x32x16_bf16 v[66:81], v[220:223], v[134:137], v[66:81]
	s_waitcnt lgkmcnt(0)
	v_mfma_f32_32x32x16_bf16 v[66:81], v[236:239], v[138:141], v[66:81]
	ds_read_b128 v[220:223], v0 offset:13120
	ds_read_b128 v[236:239], v0 offset:13152
	v_max_f32_e32 v0, v83, v83
	v_max_f32_e32 v0, v198, v0
	v_max3_f32 v0, v0, v84, v85
	v_max3_f32 v0, v0, v86, v87
	v_max3_f32 v0, v0, v88, v89
	v_max3_f32 v0, v0, v90, v91
	s_waitcnt lgkmcnt(1)
	v_mfma_f32_32x32x16_bf16 v[66:81], v[220:223], v[142:145], v[66:81]
	v_max3_f32 v0, v0, v92, v93
	v_max3_f32 v0, v0, v94, v95
	v_max3_f32 v0, v0, v96, v97
	v_xor_b32_e32 v198, 32, v230
	v_cmp_lt_i32_e32 vcc, v198, v199
	ds_read2_b64 v[220:223], v226 offset0:32 offset1:34
	s_waitcnt lgkmcnt(1)
	v_mfma_f32_32x32x16_bf16 v[66:81], v[236:239], v[146:149], v[66:81]
	v_cndmask_b32_e32 v198, v230, v198, vcc
	v_lshlrev_b32_e32 v198, 2, v198
	s_nop 9
	v_max3_f32 v0, v0, v66, v67
	v_max3_f32 v0, v0, v68, v69
	v_max3_f32 v0, v0, v70, v71
	v_max3_f32 v0, v0, v72, v73
	v_max3_f32 v0, v0, v74, v75
	v_max3_f32 v0, v0, v76, v77
	v_max3_f32 v0, v0, v78, v79
	v_max3_f32 v0, v0, v80, v81
	ds_bpermute_b32 v198, v198, v0
	s_waitcnt lgkmcnt(0)
	v_max3_f32 v219, v210, v0, v198
	v_sub_f32_e32 v0, v82, v219
	v_exp_f32_e32 v198, v0
	v_sub_f32_e32 v0, v66, v219
	v_sub_f32_e32 v66, v83, v219
	v_exp_f32_e32 v201, v66
	v_sub_f32_e32 v66, v67, v219
	v_exp_f32_e32 v203, v66
	v_sub_f32_e32 v66, v84, v219
	v_exp_f32_e32 v204, v66
	v_sub_f32_e32 v66, v68, v219
	v_exp_f32_e32 v205, v66
	v_sub_f32_e32 v66, v85, v219
	v_exp_f32_e32 v68, v66
	v_sub_f32_e32 v66, v86, v219
	v_sub_f32_e32 v82, v90, v219
	v_sub_f32_e32 v84, v92, v219
	v_exp_f32_e32 v211, v66
	v_sub_f32_e32 v66, v87, v219
	v_exp_f32_e32 v83, v82
	v_sub_f32_e32 v82, v91, v219
	v_exp_f32_e32 v85, v84
	v_sub_f32_e32 v84, v93, v219
	ds_read2_b64 v[90:93], v225 offset1:2
	v_exp_f32_e32 v202, v0
	v_sub_f32_e32 v0, v210, v219
	v_exp_f32_e32 v210, v66
	v_sub_f32_e32 v66, v88, v219
	v_exp_f32_e32 v67, v66
	v_sub_f32_e32 v66, v89, v219
	v_exp_f32_e32 v66, v66
	v_exp_f32_e32 v0, v0
	v_sub_f32_e32 v88, v96, v219
	v_add_f32_e32 v200, v198, v202
	v_sub_f32_e32 v86, v94, v219
	v_exp_f32_e32 v89, v88
	v_sub_f32_e32 v88, v97, v219
	v_cvt_pk_bf16_f32 v94, v198, v201
	v_pk_mov_b32 v[96:97], v[210:211], v[210:211] op_sel:[1,0]
	v_pk_mov_b32 v[198:199], v[66:67], v[66:67] op_sel:[1,0]
	v_exp_f32_e32 v87, v86
	v_sub_f32_e32 v86, v95, v219
	v_pk_mul_f32 v[64:65], v[64:65], v[0:1] op_sel_hi:[1,0]
	v_pk_mul_f32 v[62:63], v[62:63], v[0:1] op_sel_hi:[1,0]
	v_pk_mul_f32 v[60:61], v[60:61], v[0:1] op_sel_hi:[1,0]
	v_pk_mul_f32 v[58:59], v[58:59], v[0:1] op_sel_hi:[1,0]
	v_pk_mul_f32 v[56:57], v[56:57], v[0:1] op_sel_hi:[1,0]
	v_pk_mul_f32 v[54:55], v[54:55], v[0:1] op_sel_hi:[1,0]
	v_pk_mul_f32 v[52:53], v[52:53], v[0:1] op_sel_hi:[1,0]
	v_pk_mul_f32 v[50:51], v[50:51], v[0:1] op_sel_hi:[1,0]
	v_cvt_pk_bf16_f32 v95, v204, v68
	v_cvt_pk_bf16_f32 v96, v96, v97
	v_cvt_pk_bf16_f32 v97, v198, v199
	v_pk_mul_f32 v[48:49], v[48:49], v[0:1] op_sel_hi:[1,0]
	v_pk_mul_f32 v[46:47], v[46:47], v[0:1] op_sel_hi:[1,0]
	s_waitcnt lgkmcnt(0)
; #define LAS __attribute__((address_space(3)))
; DI unsigned pk2(float lo, float hi) { f32x2 v = {lo, hi}; bf16x2_t b = __builtin_convertvector(v, bf16x2_t); return __builtin_bit_cast(unsigned, b); }
; DI void attn_item(LAS unsigned char* lds, const Ctx& c, int bh, int qb) {
;     ...
;             const float m_new = fmaxf(m_run, mx), alpha = __builtin_amdgcn_exp2f(m_run - m_new);
;             float ps = 0.f;
; #pragma unroll
;             for (int r = 0; r < 16; ++r) { s0[r] = __builtin_amdgcn_exp2f(s0[r] - m_new); s1[r] = __builtin_amdgcn_exp2f(s1[r] - m_new); ps += s0[r] + s1[r]; }
;             l_run = l_run * alpha + ps; m_run = m_new;
; #pragma unroll
;             for (int i = 0; i < 4; ++i)
; #pragma unroll
;                 for (int r = 0; r < 16; ++r) oacc[i][r] *= alpha;
; #pragma unroll
;             for (int t = 0; t < 4; ++t) { const f32x16& sx = (t < 2) ? s0 : s1; const int o8 = 8 * (t & 1); u32x4 pw;
;                 pw.x = pk2(sx[o8 + 0], sx[o8 + 1]); pw.y = pk2(sx[o8 + 2], sx[o8 + 3]); pw.z = pk2(sx[o8 + 4], sx[o8 + 5]); pw.w = pk2(sx[o8 + 6], sx[o8 + 7]); const bf16x8 pb = __builtin_bit_cast(bf16x8, pw);
; #pragma unroll
;                 for (int md = 0; md < 4; ++md) {
;                     const LAS unsigned char* vp = Vb + (32 * md + q) * 136 + (16 * t + 4 * g) * 2;
;                     const s16x4 a = *(const LAS s16x4*)vp, bb = *(const LAS s16x4*)(vp + 16);
;                     oacc[md] = __builtin_amdgcn_mfma_f32_32x32x16_bf16(__builtin_shufflevector(a, bb, 0, 1, 2, 3, 4, 5, 6, 7), pb, oacc[md], 0, 0, 0);
;                 } }
	v_mfma_f32_32x32x16_bf16 v[50:65], v[90:93], v[94:97], v[50:65]
	ds_read2_b64 v[90:93], v228 offset0:64 offset1:66
	v_mul_f32_e64 v44, v44, v0
	v_mul_f32_e64 v45, v45, v0
	v_mul_f32_e64 v42, v42, v0
	v_mul_f32_e64 v43, v43, v0
	v_pk_mul_f32 v[40:41], v[40:41], v[0:1] op_sel_hi:[1,0]
	v_pk_mul_f32 v[38:39], v[38:39], v[0:1] op_sel_hi:[1,0]
	v_pk_mul_f32 v[36:37], v[36:37], v[0:1] op_sel_hi:[1,0]
	v_pk_mul_f32 v[34:35], v[34:35], v[0:1] op_sel_hi:[1,0]
	v_exp_f32_e32 v84, v84
	v_exp_f32_e32 v86, v86
	v_mfma_f32_32x32x16_bf16 v[34:49], v[220:223], v[94:97], v[34:49]
	ds_read2_b64 v[220:223], v224 offset0:96 offset1:98
	v_mul_f32_e64 v32, v32, v0
	v_mul_f32_e64 v33, v33, v0
	v_mul_f32_e64 v30, v30, v0
	v_mul_f32_e64 v31, v31, v0
	v_pk_mul_f32 v[28:29], v[28:29], v[0:1] op_sel_hi:[1,0]
	v_pk_mul_f32 v[26:27], v[26:27], v[0:1] op_sel_hi:[1,0]
	v_pk_mul_f32 v[24:25], v[24:25], v[0:1] op_sel_hi:[1,0]
	v_pk_mul_f32 v[22:23], v[22:23], v[0:1] op_sel_hi:[1,0]
	v_pk_mul_f32 v[20:21], v[20:21], v[0:1] op_sel_hi:[1,0]
	v_pk_mul_f32 v[18:19], v[18:19], v[0:1] op_sel_hi:[1,0]
	v_exp_f32_e32 v88, v88
	v_pk_mul_f32 v[16:17], v[16:17], v[0:1] op_sel_hi:[1,0]
	s_waitcnt lgkmcnt(1)
	v_mfma_f32_32x32x16_bf16 v[18:33], v[90:93], v[94:97], v[18:33]
	ds_read2_b64 v[90:93], v225 offset0:4 offset1:6
	v_mul_f32_e64 v14, v14, v0
	v_mul_f32_e64 v15, v15, v0
	v_mul_f32_e64 v12, v12, v0
	v_mul_f32_e64 v13, v13, v0
	v_pk_mul_f32 v[10:11], v[10:11], v[0:1] op_sel_hi:[1,0]
	v_pk_mul_f32 v[8:9], v[8:9], v[0:1] op_sel_hi:[1,0]
	v_pk_mul_f32 v[6:7], v[6:7], v[0:1] op_sel_hi:[1,0]
	v_pk_mul_f32 v[4:5], v[4:5], v[0:1] op_sel_hi:[1,0]
	v_pk_mul_f32 v[2:3], v[2:3], v[0:1] op_sel_hi:[1,0]
	v_exp_f32_e32 v82, v82
	v_sub_f32_e32 v69, v69, v219
	s_waitcnt lgkmcnt(1)
	v_mfma_f32_32x32x16_bf16 v[2:17], v[220:223], v[94:97], v[2:17]
	v_pk_mov_b32 v[94:95], v[84:85], v[84:85] op_sel:[1,0]
	v_pk_mov_b32 v[198:199], v[82:83], v[82:83] op_sel:[1,0]
	v_cvt_pk_bf16_f32 v237, v94, v95
	v_pk_mov_b32 v[94:95], v[86:87], v[86:87] op_sel:[1,0]
	v_cvt_pk_bf16_f32 v236, v198, v199
	v_cvt_pk_bf16_f32 v238, v94, v95
	v_pk_mov_b32 v[94:95], v[88:89], v[88:89] op_sel:[1,0]
	v_add_f32_e32 v199, v204, v205
	v_cvt_pk_bf16_f32 v239, v94, v95
	ds_read2_b64 v[94:97], v226 offset0:36 offset1:38
	v_exp_f32_e32 v204, v69
	s_waitcnt lgkmcnt(1)
	v_mfma_f32_32x32x16_bf16 v[50:65], v[90:93], v[236:239], v[50:65]
	v_add_f32_e32 v90, 0, v200
	v_add_f32_e32 v91, v201, v203
	v_add_f32_e32 v198, v91, v90
	ds_read2_b64 v[90:93], v228 offset0:68 offset1:70
	v_sub_f32_e32 v72, v72, v219
	v_exp_f32_e32 v201, v72
	v_sub_f32_e32 v72, v73, v219
	s_waitcnt lgkmcnt(1)
	v_mfma_f32_32x32x16_bf16 v[34:49], v[94:97], v[236:239], v[34:49]
	v_add_f32_e32 v97, v68, v204
	v_sub_f32_e32 v68, v70, v219
	v_exp_f32_e32 v95, v68
	v_sub_f32_e32 v68, v71, v219
	v_exp_f32_e32 v94, v68
	ds_read2_b64 v[68:71], v224 offset0:100 offset1:102
	v_exp_f32_e32 v200, v72
	s_waitcnt lgkmcnt(1)
	v_mfma_f32_32x32x16_bf16 v[18:33], v[90:93], v[236:239], v[18:33]
	ds_read2_b64 v[90:93], v225 offset0:8 offset1:10
	v_add_f32_e32 v96, v199, v198
	v_add_f32_e32 v220, v97, v96
	v_add_f32_e64 v198, v210, v94
	v_add_f32_e64 v199, v211, v95
	v_pk_mov_b32 v[72:73], v[200:201], v[200:201] op_sel:[1,0]
	v_sub_f32_e32 v76, v76, v219
	v_add_f32_e32 v199, v199, v220
	s_waitcnt lgkmcnt(1)
	v_mfma_f32_32x32x16_bf16 v[2:17], v[68:71], v[236:239], v[2:17]
	v_pk_mov_b32 v[70:71], v[94:95], v[94:95] op_sel:[1,0]
	ds_read2_b64 v[94:97], v226 offset0:40 offset1:42
	v_cvt_pk_bf16_f32 v68, v202, v203
	v_cvt_pk_bf16_f32 v69, v205, v204
	v_cvt_pk_bf16_f32 v70, v70, v71
	v_cvt_pk_bf16_f32 v71, v72, v73
	v_sub_f32_e32 v72, v74, v219
	v_pk_add_f32 v[66:67], v[66:67], v[200:201]
	s_waitcnt lgkmcnt(1)
	v_mfma_f32_32x32x16_bf16 v[50:65], v[90:93], v[68:71], v[50:65]
	v_exp_f32_e32 v91, v72
	v_sub_f32_e32 v72, v75, v219
	v_exp_f32_e32 v90, v72
	ds_read2_b64 v[72:75], v228 offset0:72 offset1:74
	v_exp_f32_e32 v93, v76
	v_sub_f32_e32 v76, v77, v219
	v_exp_f32_e32 v92, v76
	v_sub_f32_e32 v76, v78, v219
	s_waitcnt lgkmcnt(1)
	v_mfma_f32_32x32x16_bf16 v[34:49], v[94:97], v[68:71], v[34:49]
	v_exp_f32_e32 v95, v76
	v_sub_f32_e32 v94, v79, v219
	ds_read2_b64 v[76:79], v224 offset0:104 offset1:106
	v_exp_f32_e32 v94, v94
	v_mov_b32_e32 v210, v219
	s_waitcnt lgkmcnt(1)
	v_mfma_f32_32x32x16_bf16 v[18:33], v[72:75], v[68:71], v[18:33]
	v_sub_f32_e32 v72, v80, v219
	v_exp_f32_e32 v97, v72
	v_sub_f32_e32 v72, v81, v219
	v_exp_f32_e32 v96, v72
	ds_read2_b64 v[72:75], v225 offset0:12 offset1:14
	v_pk_mov_b32 v[80:81], v[90:91], v[90:91] op_sel:[1,0]
	s_waitcnt lgkmcnt(1)
	v_mfma_f32_32x32x16_bf16 v[2:17], v[76:79], v[68:71], v[2:17]
	v_pk_mov_b32 v[70:71], v[92:93], v[92:93] op_sel:[1,0]
	v_pk_mov_b32 v[76:77], v[96:97], v[96:97] op_sel:[1,0]
	v_cvt_pk_bf16_f32 v69, v70, v71
	v_pk_mov_b32 v[70:71], v[94:95], v[94:95] op_sel:[1,0]
	v_cvt_pk_bf16_f32 v68, v80, v81
	v_cvt_pk_bf16_f32 v70, v70, v71
	v_cvt_pk_bf16_f32 v71, v76, v77
	ds_read2_b64 v[76:79], v226 offset0:44 offset1:46
	s_waitcnt lgkmcnt(1)
	v_mfma_f32_32x32x16_bf16 v[50:65], v[72:75], v[68:71], v[50:65]
	v_add_f32_e32 v72, v198, v199
	v_add_f32_e32 v67, v67, v72
	v_add_f32_e32 v72, v66, v67
	v_add_f32_e64 v66, v82, v90
	v_add_f32_e64 v67, v83, v91
	v_add_f32_e32 v67, v67, v72
	ds_read2_b64 v[72:75], v228 offset0:76 offset1:78
	s_waitcnt lgkmcnt(1)
	v_mfma_f32_32x32x16_bf16 v[34:49], v[76:79], v[68:71], v[34:49]
	v_add_f32_e32 v76, v66, v67
	v_add_f32_e64 v66, v84, v92
	v_add_f32_e64 v67, v85, v93
	v_add_f32_e32 v67, v67, v76
	v_add_f32_e32 v76, v66, v67
	v_pk_add_f32 v[66:67], v[86:87], v[94:95]
	s_nop 0
	v_add_f32_e32 v67, v67, v76
	ds_read2_b64 v[76:79], v224 offset0:108 offset1:110
	s_waitcnt lgkmcnt(1)
	v_mfma_f32_32x32x16_bf16 v[18:33], v[72:75], v[68:71], v[18:33]
	v_add_f32_e32 v72, v66, v67
	v_add_f32_e64 v66, v88, v96
	v_add_f32_e64 v67, v89, v97
	v_add_f32_e32 v67, v67, v72
	v_add_f32_e32 v66, v66, v67
	v_fmac_f32_e32 v66, v214, v0
	v_mov_b32_e32 v214, v66
	s_waitcnt lgkmcnt(0)
	v_mfma_f32_32x32x16_bf16 v[2:17], v[76:79], v[68:71], v[2:17]
	s_andn2_b64 vcc, exec, s[8:9]
	s_cbranch_vccz .LBB0_183
	s_branch .LBB0_184
